# static priority raise for waves 4-7 kept in attention phases only (retention at equal priority)
# baseline (speedup 1.0000x reference)
.LBB0_106:
	v_readfirstlane_b32 s0, v250
	s_cmpk_lt_u32 s0, 0x100
	s_cbranch_scc1 .LBB0_109
	s_bitcmp0_b32 s74, 0
	s_cbranch_scc0 .Lprio_skip
	s_setprio 1
